# IN-GEMM epilogue: lean path for tiles without column statistics (row scales loaded up front, scale/pack/store per 16-row group)
# baseline (speedup 1.0000x reference)
.LBB0_378:
	s_andn2_b64 vcc, exec, s[44:45]
	s_cbranch_vccnz .LBB0_475
	v_ashrrev_i32_e32 v135, 31, v134
	v_lshl_add_u64 v[130:131], v[134:135], 2, s[86:87]
	global_load_dword v132, v[130:131], off
	s_cmp_lt_i32 s19, s62
	s_cselect_b64 vcc, -1, 0
	s_cmp_ge_i32 s19, s17
	v_mov_b32_e32 v0, 0x3e38aa3b
	s_cselect_b64 s[26:27], -1, 0
	s_cmp_lt_i32 s19, s63
	v_cndmask_b32_e32 v0, 1.0, v0, vcc
	s_cselect_b64 s[44:45], -1, 0
	s_and_b64 s[96:97], s[26:27], s[44:45]
	s_cmp_eq_u64 s[96:97], 0
	s_cbranch_scc1 .Lepi_fast
	s_mov_b64 s[26:27], -1
	s_and_b64 vcc, exec, s[96:97]
	s_waitcnt vmcnt(0)
	v_mul_f32_e32 v132, v0, v132
	v_pk_mul_f32 v[126:127], v[126:127], v[132:133] op_sel_hi:[1,0]
	v_pk_mul_f32 v[128:129], v[128:129], v[132:133] op_sel_hi:[1,0]
	v_pk_mul_f32 v[136:137], v[122:123], v[132:133] op_sel_hi:[1,0]
	v_pk_mul_f32 v[124:125], v[124:125], v[132:133] op_sel_hi:[1,0]
	s_cbranch_vccnz .LBB0_381
	s_mov_b64 s[26:27], 0

.Lepi_fast:
	global_load_dword v133, v[130:131], off offset:64
	global_load_dword v136, v[130:131], off offset:128
	global_load_dword v137, v[130:131], off offset:192
	global_load_dword v138, v[130:131], off offset:512
	global_load_dword v139, v[130:131], off offset:576
	global_load_dword v140, v[130:131], off offset:640
	global_load_dword v141, v[130:131], off offset:704
	s_lshl_b64 s[44:45], s[46:47], 1
	v_readlane_b32 s46, v252, 17
	v_readlane_b32 s47, v252, 18
	s_add_u32 s44, s46, s44
	s_addc_u32 s45, s47, s45
	v_add_u32_e32 v130, s48, v149
	v_ashrrev_i32_e32 v131, 31, v130
	v_lshlrev_b64 v[134:135], 12, v[134:135]
	v_lshl_add_u64 v[130:131], v[130:131], 1, s[44:45]
	s_mov_b64 s[44:45], 0x10000
	s_mov_b64 s[46:47], 0x50000
	v_lshl_add_u64 v[130:131], v[130:131], 0, v[134:135]
	s_waitcnt vmcnt(7)
	v_mul_f32_e32 v132, v0, v132
	v_mul_f32_e32 v129, v132, v129
	v_mul_f32_e32 v128, v132, v128
	v_mul_f32_e32 v127, v132, v127
	v_mul_f32_e32 v126, v132, v126
	v_mul_f32_e32 v125, v132, v125
	v_mul_f32_e32 v124, v132, v124
	v_mul_f32_e32 v123, v132, v123
	v_mul_f32_e32 v122, v132, v122
	v_mul_f32_e32 v121, v132, v121
	v_mul_f32_e32 v120, v132, v120
	v_mul_f32_e32 v119, v132, v119
	v_mul_f32_e32 v118, v132, v118
	v_mul_f32_e32 v117, v132, v117
	v_mul_f32_e32 v116, v132, v116
	v_mul_f32_e32 v115, v132, v115
	v_mul_f32_e32 v114, v132, v114
	v_cvt_pk_bf16_f32 v126, v126, v127
	v_cvt_pk_bf16_f32 v127, v128, v129
	v_cvt_pk_bf16_f32 v128, v122, v123
	v_cvt_pk_bf16_f32 v129, v124, v125
	global_store_dwordx4 v[130:131], v[126:129], off
	v_cvt_pk_bf16_f32 v118, v118, v119
	v_cvt_pk_bf16_f32 v119, v120, v121
	v_cvt_pk_bf16_f32 v120, v114, v115
	v_cvt_pk_bf16_f32 v121, v116, v117
	global_store_dwordx4 v[130:131], v[118:121], off offset:256
	v_lshl_add_u64 v[130:131], v[130:131], 0, s[44:45]
	s_waitcnt vmcnt(8)
	v_mul_f32_e32 v133, v0, v133
	v_mul_f32_e32 v113, v133, v113
	v_mul_f32_e32 v112, v133, v112
	v_mul_f32_e32 v111, v133, v111
	v_mul_f32_e32 v110, v133, v110
	v_mul_f32_e32 v109, v133, v109
	v_mul_f32_e32 v108, v133, v108
	v_mul_f32_e32 v107, v133, v107
	v_mul_f32_e32 v106, v133, v106
	v_mul_f32_e32 v105, v133, v105
	v_mul_f32_e32 v104, v133, v104
	v_mul_f32_e32 v103, v133, v103
	v_mul_f32_e32 v102, v133, v102
	v_mul_f32_e32 v101, v133, v101
	v_mul_f32_e32 v100, v133, v100
	v_mul_f32_e32 v99, v133, v99
	v_mul_f32_e32 v98, v133, v98
	v_cvt_pk_bf16_f32 v110, v110, v111
	v_cvt_pk_bf16_f32 v111, v112, v113
	v_cvt_pk_bf16_f32 v112, v106, v107
	v_cvt_pk_bf16_f32 v113, v108, v109
	global_store_dwordx4 v[130:131], v[110:113], off
	v_cvt_pk_bf16_f32 v102, v102, v103
	v_cvt_pk_bf16_f32 v103, v104, v105
	v_cvt_pk_bf16_f32 v104, v98, v99
	v_cvt_pk_bf16_f32 v105, v100, v101
	global_store_dwordx4 v[130:131], v[102:105], off offset:256
	v_lshl_add_u64 v[130:131], v[130:131], 0, s[44:45]
	s_waitcnt vmcnt(9)
	v_mul_f32_e32 v136, v0, v136
	v_mul_f32_e32 v97, v136, v97
	v_mul_f32_e32 v96, v136, v96
	v_mul_f32_e32 v95, v136, v95
	v_mul_f32_e32 v94, v136, v94
	v_mul_f32_e32 v93, v136, v93
	v_mul_f32_e32 v92, v136, v92
	v_mul_f32_e32 v91, v136, v91
	v_mul_f32_e32 v90, v136, v90
	v_mul_f32_e32 v89, v136, v89
	v_mul_f32_e32 v88, v136, v88
	v_mul_f32_e32 v87, v136, v87
	v_mul_f32_e32 v86, v136, v86
	v_mul_f32_e32 v85, v136, v85
	v_mul_f32_e32 v84, v136, v84
	v_mul_f32_e32 v83, v136, v83
	v_mul_f32_e32 v82, v136, v82
	v_cvt_pk_bf16_f32 v94, v94, v95
	v_cvt_pk_bf16_f32 v95, v96, v97
	v_cvt_pk_bf16_f32 v96, v90, v91
	v_cvt_pk_bf16_f32 v97, v92, v93
	global_store_dwordx4 v[130:131], v[94:97], off
	v_cvt_pk_bf16_f32 v86, v86, v87
	v_cvt_pk_bf16_f32 v87, v88, v89
	v_cvt_pk_bf16_f32 v88, v82, v83
	v_cvt_pk_bf16_f32 v89, v84, v85
	global_store_dwordx4 v[130:131], v[86:89], off offset:256
	v_lshl_add_u64 v[130:131], v[130:131], 0, s[44:45]
	s_waitcnt vmcnt(10)
	v_mul_f32_e32 v137, v0, v137
	v_mul_f32_e32 v81, v137, v81
	v_mul_f32_e32 v80, v137, v80
	v_mul_f32_e32 v79, v137, v79
	v_mul_f32_e32 v78, v137, v78
	v_mul_f32_e32 v77, v137, v77
	v_mul_f32_e32 v76, v137, v76
	v_mul_f32_e32 v75, v137, v75
	v_mul_f32_e32 v74, v137, v74
	v_mul_f32_e32 v73, v137, v73
	v_mul_f32_e32 v72, v137, v72
	v_mul_f32_e32 v71, v137, v71
	v_mul_f32_e32 v70, v137, v70
	v_mul_f32_e32 v69, v137, v69
	v_mul_f32_e32 v68, v137, v68
	v_mul_f32_e32 v67, v137, v67
	v_mul_f32_e32 v66, v137, v66
	v_cvt_pk_bf16_f32 v78, v78, v79
	v_cvt_pk_bf16_f32 v79, v80, v81
	v_cvt_pk_bf16_f32 v80, v74, v75
	v_cvt_pk_bf16_f32 v81, v76, v77
	global_store_dwordx4 v[130:131], v[78:81], off
	v_cvt_pk_bf16_f32 v70, v70, v71
	v_cvt_pk_bf16_f32 v71, v72, v73
	v_cvt_pk_bf16_f32 v72, v66, v67
	v_cvt_pk_bf16_f32 v73, v68, v69
	global_store_dwordx4 v[130:131], v[70:73], off offset:256
	v_lshl_add_u64 v[130:131], v[130:131], 0, s[46:47]
	s_waitcnt vmcnt(11)
	v_mul_f32_e32 v138, v0, v138
	v_mul_f32_e32 v65, v138, v65
	v_mul_f32_e32 v64, v138, v64
	v_mul_f32_e32 v63, v138, v63
	v_mul_f32_e32 v62, v138, v62
	v_mul_f32_e32 v61, v138, v61
	v_mul_f32_e32 v60, v138, v60
	v_mul_f32_e32 v59, v138, v59
	v_mul_f32_e32 v58, v138, v58
	v_mul_f32_e32 v57, v138, v57
	v_mul_f32_e32 v56, v138, v56
	v_mul_f32_e32 v55, v138, v55
	v_mul_f32_e32 v54, v138, v54
	v_mul_f32_e32 v53, v138, v53
	v_mul_f32_e32 v52, v138, v52
	v_mul_f32_e32 v51, v138, v51
	v_mul_f32_e32 v50, v138, v50
	v_cvt_pk_bf16_f32 v62, v62, v63
	v_cvt_pk_bf16_f32 v63, v64, v65
	v_cvt_pk_bf16_f32 v64, v58, v59
	v_cvt_pk_bf16_f32 v65, v60, v61
	global_store_dwordx4 v[130:131], v[62:65], off
	v_cvt_pk_bf16_f32 v54, v54, v55
	v_cvt_pk_bf16_f32 v55, v56, v57
	v_cvt_pk_bf16_f32 v56, v50, v51
	v_cvt_pk_bf16_f32 v57, v52, v53
	global_store_dwordx4 v[130:131], v[54:57], off offset:256
	v_lshl_add_u64 v[130:131], v[130:131], 0, s[44:45]
	s_waitcnt vmcnt(12)
	v_mul_f32_e32 v139, v0, v139
	v_mul_f32_e32 v49, v139, v49
	v_mul_f32_e32 v48, v139, v48
	v_mul_f32_e32 v47, v139, v47
	v_mul_f32_e32 v46, v139, v46
	v_mul_f32_e32 v45, v139, v45
	v_mul_f32_e32 v44, v139, v44
	v_mul_f32_e32 v43, v139, v43
	v_mul_f32_e32 v42, v139, v42
	v_mul_f32_e32 v41, v139, v41
	v_mul_f32_e32 v40, v139, v40
	v_mul_f32_e32 v39, v139, v39
	v_mul_f32_e32 v38, v139, v38
	v_mul_f32_e32 v37, v139, v37
	v_mul_f32_e32 v36, v139, v36
	v_mul_f32_e32 v35, v139, v35
	v_mul_f32_e32 v34, v139, v34
	v_cvt_pk_bf16_f32 v46, v46, v47
	v_cvt_pk_bf16_f32 v47, v48, v49
	v_cvt_pk_bf16_f32 v48, v42, v43
	v_cvt_pk_bf16_f32 v49, v44, v45
	global_store_dwordx4 v[130:131], v[46:49], off
	v_cvt_pk_bf16_f32 v38, v38, v39
	v_cvt_pk_bf16_f32 v39, v40, v41
	v_cvt_pk_bf16_f32 v40, v34, v35
	v_cvt_pk_bf16_f32 v41, v36, v37
	global_store_dwordx4 v[130:131], v[38:41], off offset:256
	v_lshl_add_u64 v[130:131], v[130:131], 0, s[44:45]
	s_waitcnt vmcnt(13)
	v_mul_f32_e32 v140, v0, v140
	v_mul_f32_e32 v33, v140, v33
	v_mul_f32_e32 v32, v140, v32
	v_mul_f32_e32 v31, v140, v31
	v_mul_f32_e32 v30, v140, v30
	v_mul_f32_e32 v29, v140, v29
	v_mul_f32_e32 v28, v140, v28
	v_mul_f32_e32 v27, v140, v27
	v_mul_f32_e32 v26, v140, v26
	v_mul_f32_e32 v25, v140, v25
	v_mul_f32_e32 v24, v140, v24
	v_mul_f32_e32 v23, v140, v23
	v_mul_f32_e32 v22, v140, v22
	v_mul_f32_e32 v21, v140, v21
	v_mul_f32_e32 v20, v140, v20
	v_mul_f32_e32 v19, v140, v19
	v_mul_f32_e32 v18, v140, v18
	v_cvt_pk_bf16_f32 v30, v30, v31
	v_cvt_pk_bf16_f32 v31, v32, v33
	v_cvt_pk_bf16_f32 v32, v26, v27
	v_cvt_pk_bf16_f32 v33, v28, v29
	global_store_dwordx4 v[130:131], v[30:33], off
	v_cvt_pk_bf16_f32 v22, v22, v23
	v_cvt_pk_bf16_f32 v23, v24, v25
	v_cvt_pk_bf16_f32 v24, v18, v19
	v_cvt_pk_bf16_f32 v25, v20, v21
	global_store_dwordx4 v[130:131], v[22:25], off offset:256
	v_lshl_add_u64 v[130:131], v[130:131], 0, s[44:45]
	s_waitcnt vmcnt(14)
	v_mul_f32_e32 v141, v0, v141
	v_mul_f32_e32 v17, v141, v17
	v_mul_f32_e32 v16, v141, v16
	v_mul_f32_e32 v15, v141, v15
	v_mul_f32_e32 v14, v141, v14
	v_mul_f32_e32 v13, v141, v13
	v_mul_f32_e32 v12, v141, v12
	v_mul_f32_e32 v11, v141, v11
	v_mul_f32_e32 v10, v141, v10
	v_mul_f32_e32 v9, v141, v9
	v_mul_f32_e32 v8, v141, v8
	v_mul_f32_e32 v7, v141, v7
	v_mul_f32_e32 v6, v141, v6
	v_mul_f32_e32 v5, v141, v5
	v_mul_f32_e32 v4, v141, v4
	v_mul_f32_e32 v3, v141, v3
	v_mul_f32_e32 v2, v141, v2
	v_cvt_pk_bf16_f32 v14, v14, v15
	v_cvt_pk_bf16_f32 v15, v16, v17
	v_cvt_pk_bf16_f32 v16, v10, v11
	v_cvt_pk_bf16_f32 v17, v12, v13
	global_store_dwordx4 v[130:131], v[14:17], off
	v_cvt_pk_bf16_f32 v6, v6, v7
	v_cvt_pk_bf16_f32 v7, v8, v9
	v_cvt_pk_bf16_f32 v8, v2, v3
	v_cvt_pk_bf16_f32 v9, v4, v5
	global_store_dwordx4 v[130:131], v[6:9], off offset:256
	s_branch .LBB0_475
